# grid barrier: acquire-side buffer_inv sc1 issued at barrier entry (before arrive atomic) and, for the XCD leader, after its wbl2 before the TOP arrive; post-release invalidates removed
# speedup vs baseline: 1.0282x; 1.0055x over previous
.LBB0_118:
	s_lshl_b32 s10, s14, 2
	s_add_u32 s10, s40, s10
	s_addc_u32 s11, s41, 0
	v_mov_b32_e32 v1, 0x1000
	v_mov_b32_e32 v3, 1
	buffer_inv sc1
	global_atomic_add v3, v1, v3, s[10:11] offset:1024 sc0
	v_cvt_f32_u32_e32 v1, v2
	v_sub_u32_e32 v4, 0, v2
	s_add_u32 s10, s10, 0x2400
	s_addc_u32 s11, s11, 0
	v_rcp_iflag_f32_e32 v1, v1
	s_nop 0
	v_mul_f32_e32 v1, 0x4f7ffffe, v1
	v_cvt_u32_f32_e32 v1, v1
	v_mul_lo_u32 v4, v4, v1
	v_mul_hi_u32 v4, v1, v4
	v_add_u32_e32 v1, v1, v4
	s_waitcnt vmcnt(0)
	v_mul_hi_u32 v1, v3, v1
	v_mul_lo_u32 v4, v1, v2
	v_sub_u32_e32 v4, v3, v4
	v_add_u32_e32 v5, 1, v1
	v_cmp_ge_u32_e32 vcc, v4, v2
	v_add_u32_e32 v3, 1, v3
	s_nop 0
	v_cndmask_b32_e32 v1, v1, v5, vcc
	v_sub_u32_e32 v5, v4, v2
	v_cndmask_b32_e32 v4, v4, v5, vcc
	v_add_u32_e32 v5, 1, v1
	v_cmp_ge_u32_e32 vcc, v4, v2
	s_nop 1
	v_cndmask_b32_e32 v1, v1, v5, vcc
	v_mul_lo_u32 v4, v2, v1
	v_add_u32_e32 v2, v4, v2
	v_cmp_ne_u32_e32 vcc, v3, v2
	s_and_saveexec_b64 s[12:13], vcc
	s_xor_b64 s[12:13], exec, s[12:13]
	s_cbranch_execz .LBB0_132
	s_waitcnt lgkmcnt(0)
	v_mov_b32_e32 v0, 0
	global_load_dword v2, v0, s[10:11] sc1
	s_waitcnt vmcnt(0)
	v_cmp_eq_u32_e32 vcc, v2, v1
	s_and_saveexec_b64 s[16:17], vcc
	s_cbranch_execz .LBB0_131
	s_mov_b32 s28, 1
	s_mov_b64 s[18:19], 0
	s_branch .LBB0_122

.LBB0_131:
	s_or_b64 exec, exec, s[16:17]
	s_waitcnt vmcnt(0)
	s_waitcnt vmcnt(0)
.LBB0_132:
	s_andn2_saveexec_b64 s[12:13], s[12:13]
	s_cbranch_execz .LBB0_150
	s_mov_b64 s[12:13], exec
	buffer_wbl2 sc1
	s_waitcnt lgkmcnt(0)
	s_waitcnt vmcnt(0)
	v_mbcnt_lo_u32_b32 v1, s12, 0
	v_mbcnt_hi_u32_b32 v1, s13, v1
	v_cmp_eq_u32_e32 vcc, 0, v1
	s_and_saveexec_b64 s[16:17], vcc
	s_cbranch_execz .LBB0_135
	s_bcnt1_i32_b64 s12, s[12:13]
	v_mov_b32_e32 v2, 0x13763000
	v_mov_b32_e32 v3, s12
	buffer_inv sc1
	global_atomic_add v2, v2, v3, s[0:1] offset:3072 sc0

.LBB0_149:
	s_or_b64 exec, exec, s[8:9]
	v_mov_b32_e32 v0, 0
	v_mov_b32_e32 v1, 1
	s_waitcnt vmcnt(0)
	global_atomic_add v0, v1, s[10:11]
	s_waitcnt vmcnt(0)

.LBB0_209:
	v_readlane_b32 s2, v255, 6
	v_readlane_b32 s3, v255, 7
	v_mov_b32_e32 v1, 1
	v_sub_u32_e32 v4, 0, v2
	s_nop 2
	buffer_inv sc1
	global_atomic_add v3, v97, v1, s[2:3] sc0
	v_cvt_f32_u32_e32 v1, v2
	v_rcp_iflag_f32_e32 v1, v1
	s_nop 0
	v_mul_f32_e32 v1, 0x4f7ffffe, v1
	v_cvt_u32_f32_e32 v1, v1
	v_mul_lo_u32 v4, v4, v1
	v_mul_hi_u32 v4, v1, v4
	v_add_u32_e32 v1, v1, v4
	s_waitcnt vmcnt(0)
	v_mul_hi_u32 v1, v3, v1
	v_mul_lo_u32 v4, v1, v2
	v_sub_u32_e32 v4, v3, v4
	v_add_u32_e32 v5, 1, v1
	v_cmp_ge_u32_e32 vcc, v4, v2
	v_add_u32_e32 v3, 1, v3
	s_nop 0
	v_cndmask_b32_e32 v1, v1, v5, vcc
	v_sub_u32_e32 v5, v4, v2
	v_cndmask_b32_e32 v4, v4, v5, vcc
	v_add_u32_e32 v5, 1, v1
	v_cmp_ge_u32_e32 vcc, v4, v2
	s_nop 1
	v_cndmask_b32_e32 v1, v1, v5, vcc
	v_mul_lo_u32 v4, v2, v1
	v_add_u32_e32 v2, v4, v2
	v_cmp_ne_u32_e32 vcc, v3, v2
	s_and_saveexec_b64 s[2:3], vcc
	s_xor_b64 s[42:43], exec, s[2:3]
	s_cbranch_execz .LBB0_223
	v_readlane_b32 s2, v255, 8
	v_readlane_b32 s3, v255, 9
	s_waitcnt lgkmcnt(0)
	s_nop 3
	global_load_dword v0, v97, s[2:3] sc1
	s_waitcnt vmcnt(0)
	v_cmp_eq_u32_e32 vcc, v0, v1
	s_and_saveexec_b64 s[44:45], vcc
	s_cbranch_execz .LBB0_222
	s_mov_b32 s2, 1
	s_mov_b64 s[46:47], 0
	s_branch .LBB0_213

.LBB0_222:
	s_or_b64 exec, exec, s[44:45]
	s_waitcnt vmcnt(0)
	s_waitcnt vmcnt(0)
.LBB0_223:
	s_andn2_saveexec_b64 s[2:3], s[42:43]
	s_cbranch_execz .LBB0_241
	s_mov_b64 s[42:43], exec
	buffer_wbl2 sc1
	s_waitcnt lgkmcnt(0)
	s_waitcnt vmcnt(0)
	v_mbcnt_lo_u32_b32 v1, s42, 0
	v_mbcnt_hi_u32_b32 v1, s43, v1
	v_cmp_eq_u32_e32 vcc, 0, v1
	s_and_saveexec_b64 s[44:45], vcc
	s_cbranch_execz .LBB0_226
	s_bcnt1_i32_b64 s2, s[42:43]
	v_mov_b32_e32 v2, s2
	v_readlane_b32 s2, v255, 10
	v_readlane_b32 s3, v255, 11
	s_nop 4
	buffer_inv sc1
	global_atomic_add v2, v97, v2, s[2:3] sc0

.LBB0_240:
	s_or_b64 exec, exec, s[42:43]
	v_readlane_b32 s2, v255, 8
	v_readlane_b32 s3, v255, 9
	v_mov_b32_e32 v0, 1
	s_waitcnt vmcnt(0)
	s_nop 1
	global_atomic_add v97, v0, s[2:3]
	s_waitcnt vmcnt(0)

.LBB0_530:
	s_andn2_saveexec_b64 s[2:3], s[42:43]
	s_cbranch_execz .LBB0_548
	s_mov_b64 s[42:43], exec
	v_mov_b32_e32 v1, 0x20810
	ds_read_b32 v1, v1
	s_waitcnt lgkmcnt(0)
	v_readfirstlane_b32 s2, v1
	s_cmp_lg_u32 s2, 0
	s_cbranch_scc1 .Lxl_fin_skip
	buffer_wbl2 sc1
	s_waitcnt lgkmcnt(0)
	s_waitcnt vmcnt(0)
	v_mbcnt_lo_u32_b32 v1, s42, 0
	v_mbcnt_hi_u32_b32 v1, s43, v1
	v_cmp_eq_u32_e32 vcc, 0, v1
	s_and_saveexec_b64 s[44:45], vcc
	s_cbranch_execz .LBB0_533
	s_bcnt1_i32_b64 s2, s[42:43]
	v_mov_b32_e32 v2, s2
	v_readlane_b32 s2, v255, 10
	v_readlane_b32 s3, v255, 11
	s_nop 4
	buffer_inv sc1
	global_atomic_add v2, v97, v2, s[2:3] sc0

.Lxl_fin_skip:
	v_readlane_b32 s2, v255, 8
	v_readlane_b32 s3, v255, 9
	v_mov_b32_e32 v0, 1
	s_waitcnt vmcnt(0)
	s_nop 1
	global_atomic_add v97, v0, s[2:3]
	s_waitcnt vmcnt(0)

.LBB0_706:
	v_readlane_b32 s4, v255, 6
	v_readlane_b32 s5, v255, 7
	v_mov_b32_e32 v1, 1
	v_sub_u32_e32 v4, 0, v2
	s_nop 2
	buffer_inv sc1
	global_atomic_add v3, v97, v1, s[4:5] sc0
	v_cvt_f32_u32_e32 v1, v2
	v_rcp_iflag_f32_e32 v1, v1
	s_nop 0
	v_mul_f32_e32 v1, 0x4f7ffffe, v1
	v_cvt_u32_f32_e32 v1, v1
	v_mul_lo_u32 v4, v4, v1
	v_mul_hi_u32 v4, v1, v4
	v_add_u32_e32 v1, v1, v4
	s_waitcnt vmcnt(0)
	v_mul_hi_u32 v1, v3, v1
	v_mul_lo_u32 v4, v1, v2
	v_sub_u32_e32 v4, v3, v4
	v_add_u32_e32 v5, 1, v1
	v_cmp_ge_u32_e32 vcc, v4, v2
	v_add_u32_e32 v3, 1, v3
	s_nop 0
	v_cndmask_b32_e32 v1, v1, v5, vcc
	v_sub_u32_e32 v5, v4, v2
	v_cndmask_b32_e32 v4, v4, v5, vcc
	v_add_u32_e32 v5, 1, v1
	v_cmp_ge_u32_e32 vcc, v4, v2
	s_nop 1
	v_cndmask_b32_e32 v1, v1, v5, vcc
	v_mul_lo_u32 v4, v2, v1
	v_add_u32_e32 v2, v4, v2
	v_cmp_ne_u32_e32 vcc, v3, v2
	s_and_saveexec_b64 s[4:5], vcc
	s_xor_b64 s[42:43], exec, s[4:5]
	s_cbranch_execz .LBB0_720
	v_readlane_b32 s4, v255, 8
	v_readlane_b32 s5, v255, 9
	s_waitcnt lgkmcnt(0)
	s_nop 3
	global_load_dword v0, v97, s[4:5] sc1
	s_waitcnt vmcnt(0)
	v_cmp_eq_u32_e32 vcc, v0, v1
	s_and_saveexec_b64 s[44:45], vcc
	s_cbranch_execz .LBB0_719
	s_mov_b32 s3, 1
	s_mov_b64 s[46:47], 0
	s_branch .LBB0_710

.LBB0_720:
	s_andn2_saveexec_b64 s[4:5], s[42:43]
	s_cbranch_execz .LBB0_738
	s_mov_b64 s[42:43], exec
	buffer_wbl2 sc1
	s_waitcnt lgkmcnt(0)
	s_waitcnt vmcnt(0)
	v_mbcnt_lo_u32_b32 v1, s42, 0
	v_mbcnt_hi_u32_b32 v1, s43, v1
	v_cmp_eq_u32_e32 vcc, 0, v1
	s_and_saveexec_b64 s[44:45], vcc
	s_cbranch_execz .LBB0_723
	s_bcnt1_i32_b64 s3, s[42:43]
	v_readlane_b32 s4, v255, 10
	v_mov_b32_e32 v2, s3
	v_readlane_b32 s5, v255, 11
	s_nop 4
	buffer_inv sc1
	global_atomic_add v2, v97, v2, s[4:5] sc0

.LBB0_737:
	s_or_b64 exec, exec, s[42:43]
	v_readlane_b32 s4, v255, 8
	v_readlane_b32 s5, v255, 9
	v_mov_b32_e32 v0, 1
	s_waitcnt vmcnt(0)
	s_nop 1
	global_atomic_add v97, v0, s[4:5]
	s_waitcnt vmcnt(0)

.Lxl_fout_no:
	buffer_wbl2 sc1
	s_waitcnt lgkmcnt(0)
	s_waitcnt vmcnt(0)
	v_mbcnt_lo_u32_b32 v1, s42, 0
	v_mbcnt_hi_u32_b32 v1, s43, v1
	v_cmp_eq_u32_e32 vcc, 0, v1
	s_and_saveexec_b64 s[44:45], vcc
	s_cbranch_execz .LBB0_964
	s_bcnt1_i32_b64 s2, s[42:43]
	v_mov_b32_e32 v2, s2
	v_readlane_b32 s2, v255, 10
	v_readlane_b32 s3, v255, 11
	s_nop 4
	buffer_inv sc1
	global_atomic_add v2, v97, v2, s[2:3] sc0

.LBB0_1209:
	v_readlane_b32 s2, v255, 6
	v_mov_b32_e32 v3, 0
	v_mov_b32_e32 v1, 1
	v_readlane_b32 s3, v255, 7
	v_sub_u32_e32 v5, 0, v2
	s_nop 3
	buffer_inv sc1
	global_atomic_add v4, v3, v1, s[2:3] sc0
	v_cvt_f32_u32_e32 v1, v2
	v_rcp_iflag_f32_e32 v1, v1
	s_nop 0
	v_mul_f32_e32 v1, 0x4f7ffffe, v1
	v_cvt_u32_f32_e32 v1, v1
	v_mul_lo_u32 v5, v5, v1
	v_mul_hi_u32 v5, v1, v5
	v_add_u32_e32 v1, v1, v5
	s_waitcnt vmcnt(0)
	v_mul_hi_u32 v1, v4, v1
	v_mul_lo_u32 v5, v1, v2
	v_sub_u32_e32 v5, v4, v5
	v_add_u32_e32 v6, 1, v1
	v_cmp_ge_u32_e32 vcc, v5, v2
	v_add_u32_e32 v4, 1, v4
	s_nop 0
	v_cndmask_b32_e32 v1, v1, v6, vcc
	v_sub_u32_e32 v6, v5, v2
	v_cndmask_b32_e32 v5, v5, v6, vcc
	v_add_u32_e32 v6, 1, v1
	v_cmp_ge_u32_e32 vcc, v5, v2
	s_nop 1
	v_cndmask_b32_e32 v1, v1, v6, vcc
	v_mul_lo_u32 v5, v2, v1
	v_add_u32_e32 v2, v5, v2
	v_cmp_ne_u32_e32 vcc, v4, v2
	s_and_saveexec_b64 s[2:3], vcc
	s_xor_b64 s[2:3], exec, s[2:3]
	s_cbranch_execz .LBB0_1223
	v_readlane_b32 s4, v255, 8
	v_readlane_b32 s5, v255, 9
	s_waitcnt lgkmcnt(0)
	s_nop 3
	global_load_dword v0, v3, s[4:5] sc1
	s_waitcnt vmcnt(0)
	v_cmp_eq_u32_e32 vcc, v0, v1
	s_and_saveexec_b64 s[4:5], vcc
	s_cbranch_execz .LBB0_1222
	s_mov_b32 s16, 1
	s_mov_b64 s[6:7], 0
	v_mov_b32_e32 v0, 0
	s_branch .LBB0_1213

.LBB0_1222:
	s_or_b64 exec, exec, s[4:5]
	s_waitcnt vmcnt(0)
	s_waitcnt vmcnt(0)
.LBB0_1223:
	s_andn2_saveexec_b64 s[2:3], s[2:3]
	s_cbranch_execz .LBB0_1241
	s_mov_b64 s[2:3], exec
	v_mov_b32_e32 v1, 0x20810
	ds_read_b32 v1, v1
	s_waitcnt lgkmcnt(0)
	v_readfirstlane_b32 s4, v1
	s_cmp_lg_u32 s4, 0
	s_cbranch_scc1 .Lxl_final_skip
	buffer_wbl2 sc1
	s_waitcnt lgkmcnt(0)
	s_waitcnt vmcnt(0)
	v_mbcnt_lo_u32_b32 v1, s2, 0
	v_mbcnt_hi_u32_b32 v1, s3, v1
	v_cmp_eq_u32_e32 vcc, 0, v1
	s_and_saveexec_b64 s[4:5], vcc
	s_cbranch_execz .LBB0_1226
	s_bcnt1_i32_b64 s2, s[2:3]
	v_mov_b32_e32 v3, s2
	v_readlane_b32 s2, v255, 10
	v_mov_b32_e32 v2, 0
	v_readlane_b32 s3, v255, 11
	s_nop 4
	buffer_inv sc1
	global_atomic_add v2, v2, v3, s[2:3] sc0

.Lxl_final_skip:
	v_readlane_b32 s2, v255, 8
	v_mov_b32_e32 v0, 0
	v_mov_b32_e32 v1, 1
	v_readlane_b32 s3, v255, 9
	s_waitcnt vmcnt(0)
	s_nop 2
	global_atomic_add v0, v1, s[2:3]
	s_waitcnt vmcnt(0)
